# phase 2 start staggered by row-tile group inside each XCD (8 offsets of about 3 us): epilogue store bursts of the 32 workgroups of an XCD no longer coincide
# speedup vs baseline: 1.0227x; 1.0101x over previous
.LBB0_174:
	s_cmp_lt_i32 s24, 3
	s_cselect_b64 s[12:13], -1, 0
	s_and_b64 s[4:5], s[12:13], s[4:5]
	s_andn2_b64 vcc, exec, s[4:5]
	s_cbranch_vccnz .LBB0_207
	s_lshr_b32 s98, s2, 3
	s_and_b32 s98, s98, 7
	s_cmp_eq_u32 s98, 0
	s_cbranch_scc1 .Lstg_go175
